# hand-written V^T epilogue for the non-dilated value tiles of P1: 8x8 in-register transpose (DPP) so each lane stores one 16-byte fragment chunk instead of eight 2-byte scattered stores
# baseline (speedup 1.0000x reference)
.Lvt0:
	v_readfirstlane_b32 s32, v236
	s_bfe_u32 s32, s32, 0x20006
	s_lshr_b32 s55, s58, 3
	s_mul_i32 s55, s55, 24
	s_add_i32 s55, s55, s67
	s_lshr_b32 s57, s32, 1
	s_add_i32 s55, s55, s57
	s_lshr_b32 s101, s55, 14
	s_lshl_b32 s100, s55, 18
	s_add_u32 s100, s100, s16
	s_addc_u32 s101, s101, s17
	s_and_b32 s57, s58, 7
	s_lshl_b32 s57, s57, 15
	s_lshl_b32 s92, s83, 7
	s_add_i32 s57, s57, s92
	s_and_b32 s92, s32, 1
	s_lshl_b32 s92, s92, 11
	s_add_i32 s57, s57, s92
	s_add_u32 s100, s100, s57
	s_addc_u32 s101, s101, 0
	v_and_b32_e32 v188, 8, v143
	v_and_b32_e32 v189, 2, v143
	v_cmp_ne_u32_e64 s[6:7], 0, v188
	v_cmp_ne_u32_e64 s[80:81], 0, v189
	v_and_b32_e32 v188, 1, v143
	v_mov_b32_e32 v189, 0x5040100
	v_mov_b32_e32 v182, 0x3020706
	v_cmp_ne_u32_e32 vcc, 0, v188
	s_not_b64 s[64:65], s[6:7]
	s_not_b64 s[98:99], s[80:81]
	v_cndmask_b32_e32 v182, v189, v182, vcc
	v_lshrrev_b32_e32 v188, 1, v143
	v_and_b32_e32 v189, 3, v143
	v_and_or_b32 v188, v188, 4, v189
	v_and_b32_e32 v189, 31, v142
	v_add_lshl_u32 v188, v188, v189, 4
	v_and_b32_e32 v189, 4, v143
	v_lshl_add_u32 v183, v189, 7, v188
	v_pk_mul_f32 v[126:127], v[126:127], v[156:157] op_sel_hi:[1,0]
	v_pk_mul_f32 v[128:129], v[128:129], v[156:157] op_sel_hi:[1,0]
	v_pk_mul_f32 v[122:123], v[122:123], v[156:157] op_sel_hi:[1,0]
	v_pk_mul_f32 v[124:125], v[124:125], v[156:157] op_sel_hi:[1,0]
	v_pk_mul_f32 v[118:119], v[118:119], v[156:157] op_sel_hi:[1,0]
	v_pk_mul_f32 v[120:121], v[120:121], v[156:157] op_sel_hi:[1,0]
	v_pk_mul_f32 v[114:115], v[114:115], v[156:157] op_sel_hi:[1,0]
	v_pk_mul_f32 v[116:117], v[116:117], v[156:157] op_sel_hi:[1,0]
	v_pk_mul_f32 v[110:111], v[110:111], v[158:159] op_sel_hi:[1,0]
	v_pk_mul_f32 v[112:113], v[112:113], v[158:159] op_sel_hi:[1,0]
	v_pk_mul_f32 v[106:107], v[106:107], v[158:159] op_sel_hi:[1,0]
	v_pk_mul_f32 v[108:109], v[108:109], v[158:159] op_sel_hi:[1,0]
	v_pk_mul_f32 v[102:103], v[102:103], v[158:159] op_sel_hi:[1,0]
	v_pk_mul_f32 v[104:105], v[104:105], v[158:159] op_sel_hi:[1,0]
	v_pk_mul_f32 v[98:99], v[98:99], v[158:159] op_sel_hi:[1,0]
	v_pk_mul_f32 v[100:101], v[100:101], v[158:159] op_sel_hi:[1,0]
	v_pk_mul_f32 v[94:95], v[94:95], v[160:161] op_sel_hi:[1,0]
	v_pk_mul_f32 v[96:97], v[96:97], v[160:161] op_sel_hi:[1,0]
	v_pk_mul_f32 v[90:91], v[90:91], v[160:161] op_sel_hi:[1,0]
	v_pk_mul_f32 v[92:93], v[92:93], v[160:161] op_sel_hi:[1,0]
	v_pk_mul_f32 v[86:87], v[86:87], v[160:161] op_sel_hi:[1,0]
	v_pk_mul_f32 v[88:89], v[88:89], v[160:161] op_sel_hi:[1,0]
	v_pk_mul_f32 v[82:83], v[82:83], v[160:161] op_sel_hi:[1,0]
	v_pk_mul_f32 v[84:85], v[84:85], v[160:161] op_sel_hi:[1,0]
	v_pk_mul_f32 v[78:79], v[78:79], v[162:163] op_sel_hi:[1,0]
	v_pk_mul_f32 v[80:81], v[80:81], v[162:163] op_sel_hi:[1,0]
	v_pk_mul_f32 v[74:75], v[74:75], v[162:163] op_sel_hi:[1,0]
	v_pk_mul_f32 v[76:77], v[76:77], v[162:163] op_sel_hi:[1,0]
	v_pk_mul_f32 v[70:71], v[70:71], v[162:163] op_sel_hi:[1,0]
	v_pk_mul_f32 v[72:73], v[72:73], v[162:163] op_sel_hi:[1,0]
	v_pk_mul_f32 v[66:67], v[66:67], v[162:163] op_sel_hi:[1,0]
	v_pk_mul_f32 v[68:69], v[68:69], v[162:163] op_sel_hi:[1,0]
	v_pk_mul_f32 v[62:63], v[62:63], v[164:165] op_sel_hi:[1,0]
	v_pk_mul_f32 v[64:65], v[64:65], v[164:165] op_sel_hi:[1,0]
	v_pk_mul_f32 v[58:59], v[58:59], v[164:165] op_sel_hi:[1,0]
	v_pk_mul_f32 v[60:61], v[60:61], v[164:165] op_sel_hi:[1,0]
	v_pk_mul_f32 v[54:55], v[54:55], v[164:165] op_sel_hi:[1,0]
	v_pk_mul_f32 v[56:57], v[56:57], v[164:165] op_sel_hi:[1,0]
	v_pk_mul_f32 v[50:51], v[50:51], v[164:165] op_sel_hi:[1,0]
	v_pk_mul_f32 v[52:53], v[52:53], v[164:165] op_sel_hi:[1,0]
	v_pk_mul_f32 v[46:47], v[46:47], v[166:167] op_sel_hi:[1,0]
	v_pk_mul_f32 v[48:49], v[48:49], v[166:167] op_sel_hi:[1,0]
	v_pk_mul_f32 v[42:43], v[42:43], v[166:167] op_sel_hi:[1,0]
	v_pk_mul_f32 v[44:45], v[44:45], v[166:167] op_sel_hi:[1,0]
	v_pk_mul_f32 v[38:39], v[38:39], v[166:167] op_sel_hi:[1,0]
	v_pk_mul_f32 v[40:41], v[40:41], v[166:167] op_sel_hi:[1,0]
	v_pk_mul_f32 v[34:35], v[34:35], v[166:167] op_sel_hi:[1,0]
	v_pk_mul_f32 v[36:37], v[36:37], v[166:167] op_sel_hi:[1,0]
	v_pk_mul_f32 v[30:31], v[30:31], v[168:169] op_sel_hi:[1,0]
	v_pk_mul_f32 v[32:33], v[32:33], v[168:169] op_sel_hi:[1,0]
	v_pk_mul_f32 v[26:27], v[26:27], v[168:169] op_sel_hi:[1,0]
	v_pk_mul_f32 v[28:29], v[28:29], v[168:169] op_sel_hi:[1,0]
	v_pk_mul_f32 v[22:23], v[22:23], v[168:169] op_sel_hi:[1,0]
	v_pk_mul_f32 v[24:25], v[24:25], v[168:169] op_sel_hi:[1,0]
	v_pk_mul_f32 v[18:19], v[18:19], v[168:169] op_sel_hi:[1,0]
	v_pk_mul_f32 v[20:21], v[20:21], v[168:169] op_sel_hi:[1,0]
	v_pk_mul_f32 v[14:15], v[14:15], v[170:171] op_sel_hi:[1,0]
	v_pk_mul_f32 v[16:17], v[16:17], v[170:171] op_sel_hi:[1,0]
	v_pk_mul_f32 v[10:11], v[10:11], v[170:171] op_sel_hi:[1,0]
	v_pk_mul_f32 v[12:13], v[12:13], v[170:171] op_sel_hi:[1,0]
	v_pk_mul_f32 v[6:7], v[6:7], v[170:171] op_sel_hi:[1,0]
	v_pk_mul_f32 v[8:9], v[8:9], v[170:171] op_sel_hi:[1,0]
	v_pk_mul_f32 v[2:3], v[2:3], v[170:171] op_sel_hi:[1,0]
	v_pk_mul_f32 v[4:5], v[4:5], v[170:171] op_sel_hi:[1,0]
	v_cvt_pk_bf16_f32 v126, v126, v127
	v_cvt_pk_bf16_f32 v127, v128, v129
	v_cvt_pk_bf16_f32 v128, v122, v123
	v_cvt_pk_bf16_f32 v129, v124, v125
	v_cvt_pk_bf16_f32 v118, v118, v119
	v_cvt_pk_bf16_f32 v119, v120, v121
	v_cvt_pk_bf16_f32 v120, v114, v115
	v_cvt_pk_bf16_f32 v121, v116, v117
	v_cvt_pk_bf16_f32 v110, v110, v111
	v_cvt_pk_bf16_f32 v111, v112, v113
	v_cvt_pk_bf16_f32 v112, v106, v107
	v_cvt_pk_bf16_f32 v113, v108, v109
	v_cvt_pk_bf16_f32 v102, v102, v103
	v_cvt_pk_bf16_f32 v103, v104, v105
	v_cvt_pk_bf16_f32 v104, v98, v99
	v_cvt_pk_bf16_f32 v105, v100, v101
	v_cvt_pk_bf16_f32 v94, v94, v95
	v_cvt_pk_bf16_f32 v95, v96, v97
	v_cvt_pk_bf16_f32 v96, v90, v91
	v_cvt_pk_bf16_f32 v97, v92, v93
	v_cvt_pk_bf16_f32 v86, v86, v87
	v_cvt_pk_bf16_f32 v87, v88, v89
	v_cvt_pk_bf16_f32 v88, v82, v83
	v_cvt_pk_bf16_f32 v89, v84, v85
	v_cvt_pk_bf16_f32 v78, v78, v79
	v_cvt_pk_bf16_f32 v79, v80, v81
	v_cvt_pk_bf16_f32 v80, v74, v75
	v_cvt_pk_bf16_f32 v81, v76, v77
	v_cvt_pk_bf16_f32 v70, v70, v71
	v_cvt_pk_bf16_f32 v71, v72, v73
	v_cvt_pk_bf16_f32 v72, v66, v67
	v_cvt_pk_bf16_f32 v73, v68, v69
	v_cvt_pk_bf16_f32 v62, v62, v63
	v_cvt_pk_bf16_f32 v63, v64, v65
	v_cvt_pk_bf16_f32 v64, v58, v59
	v_cvt_pk_bf16_f32 v65, v60, v61
	v_cvt_pk_bf16_f32 v54, v54, v55
	v_cvt_pk_bf16_f32 v55, v56, v57
	v_cvt_pk_bf16_f32 v56, v50, v51
	v_cvt_pk_bf16_f32 v57, v52, v53
	v_cvt_pk_bf16_f32 v46, v46, v47
	v_cvt_pk_bf16_f32 v47, v48, v49
	v_cvt_pk_bf16_f32 v48, v42, v43
	v_cvt_pk_bf16_f32 v49, v44, v45
	v_cvt_pk_bf16_f32 v38, v38, v39
	v_cvt_pk_bf16_f32 v39, v40, v41
	v_cvt_pk_bf16_f32 v40, v34, v35
	v_cvt_pk_bf16_f32 v41, v36, v37
	v_cvt_pk_bf16_f32 v30, v30, v31
	v_cvt_pk_bf16_f32 v31, v32, v33
	v_cvt_pk_bf16_f32 v32, v26, v27
	v_cvt_pk_bf16_f32 v33, v28, v29
	v_cvt_pk_bf16_f32 v22, v22, v23
	v_cvt_pk_bf16_f32 v23, v24, v25
	v_cvt_pk_bf16_f32 v24, v18, v19
	v_cvt_pk_bf16_f32 v25, v20, v21
	v_cvt_pk_bf16_f32 v14, v14, v15
	v_cvt_pk_bf16_f32 v15, v16, v17
	v_cvt_pk_bf16_f32 v16, v10, v11
	v_cvt_pk_bf16_f32 v17, v12, v13
	v_cvt_pk_bf16_f32 v6, v6, v7
	v_cvt_pk_bf16_f32 v7, v8, v9
	v_cvt_pk_bf16_f32 v8, v2, v3
	v_cvt_pk_bf16_f32 v9, v4, v5
	v_cndmask_b32_e64 v122, v128, v126, s[6:7]
	v_cndmask_b32_e64 v123, v129, v127, s[6:7]
	v_cndmask_b32_e64 v114, v120, v118, s[6:7]
	v_cndmask_b32_e64 v115, v121, v119, s[6:7]
	v_cndmask_b32_e64 v106, v112, v110, s[6:7]
	v_cndmask_b32_e64 v107, v113, v111, s[6:7]
	v_cndmask_b32_e64 v98, v104, v102, s[6:7]
	v_cndmask_b32_e64 v99, v105, v103, s[6:7]
	v_cndmask_b32_e64 v90, v96, v94, s[6:7]
	v_cndmask_b32_e64 v91, v97, v95, s[6:7]
	v_cndmask_b32_e64 v82, v88, v86, s[6:7]
	v_cndmask_b32_e64 v83, v89, v87, s[6:7]
	v_cndmask_b32_e64 v74, v80, v78, s[6:7]
	v_cndmask_b32_e64 v75, v81, v79, s[6:7]
	v_cndmask_b32_e64 v66, v72, v70, s[6:7]
	v_cndmask_b32_e64 v67, v73, v71, s[6:7]
	v_cndmask_b32_e64 v58, v64, v62, s[6:7]
	v_cndmask_b32_e64 v59, v65, v63, s[6:7]
	v_cndmask_b32_e64 v50, v56, v54, s[6:7]
	v_cndmask_b32_e64 v51, v57, v55, s[6:7]
	v_cndmask_b32_e64 v42, v48, v46, s[6:7]
	v_cndmask_b32_e64 v43, v49, v47, s[6:7]
	v_cndmask_b32_e64 v34, v40, v38, s[6:7]
	v_cndmask_b32_e64 v35, v41, v39, s[6:7]
	v_cndmask_b32_e64 v26, v32, v30, s[6:7]
	v_cndmask_b32_e64 v27, v33, v31, s[6:7]
	v_cndmask_b32_e64 v18, v24, v22, s[6:7]
	v_cndmask_b32_e64 v19, v25, v23, s[6:7]
	v_cndmask_b32_e64 v10, v16, v14, s[6:7]
	v_cndmask_b32_e64 v11, v17, v15, s[6:7]
	v_cndmask_b32_e64 v2, v8, v6, s[6:7]
	v_cndmask_b32_e64 v3, v9, v7, s[6:7]
	s_mov_b64 vcc, s[6:7]
	s_nop 1
	v_cndmask_b32_dpp v128, v122, v128, vcc row_ror:8 row_mask:0xf bank_mask:0xf
	v_cndmask_b32_dpp v129, v123, v129, vcc row_ror:8 row_mask:0xf bank_mask:0xf
	v_cndmask_b32_dpp v120, v114, v120, vcc row_ror:8 row_mask:0xf bank_mask:0xf
	v_cndmask_b32_dpp v121, v115, v121, vcc row_ror:8 row_mask:0xf bank_mask:0xf
	v_cndmask_b32_dpp v112, v106, v112, vcc row_ror:8 row_mask:0xf bank_mask:0xf
	v_cndmask_b32_dpp v113, v107, v113, vcc row_ror:8 row_mask:0xf bank_mask:0xf
	v_cndmask_b32_dpp v104, v98, v104, vcc row_ror:8 row_mask:0xf bank_mask:0xf
	v_cndmask_b32_dpp v105, v99, v105, vcc row_ror:8 row_mask:0xf bank_mask:0xf
	v_cndmask_b32_dpp v96, v90, v96, vcc row_ror:8 row_mask:0xf bank_mask:0xf
	v_cndmask_b32_dpp v97, v91, v97, vcc row_ror:8 row_mask:0xf bank_mask:0xf
	v_cndmask_b32_dpp v88, v82, v88, vcc row_ror:8 row_mask:0xf bank_mask:0xf
	v_cndmask_b32_dpp v89, v83, v89, vcc row_ror:8 row_mask:0xf bank_mask:0xf
	v_cndmask_b32_dpp v80, v74, v80, vcc row_ror:8 row_mask:0xf bank_mask:0xf
	v_cndmask_b32_dpp v81, v75, v81, vcc row_ror:8 row_mask:0xf bank_mask:0xf
	v_cndmask_b32_dpp v72, v66, v72, vcc row_ror:8 row_mask:0xf bank_mask:0xf
	v_cndmask_b32_dpp v73, v67, v73, vcc row_ror:8 row_mask:0xf bank_mask:0xf
	v_cndmask_b32_dpp v64, v58, v64, vcc row_ror:8 row_mask:0xf bank_mask:0xf
	v_cndmask_b32_dpp v65, v59, v65, vcc row_ror:8 row_mask:0xf bank_mask:0xf
	v_cndmask_b32_dpp v56, v50, v56, vcc row_ror:8 row_mask:0xf bank_mask:0xf
	v_cndmask_b32_dpp v57, v51, v57, vcc row_ror:8 row_mask:0xf bank_mask:0xf
	v_cndmask_b32_dpp v48, v42, v48, vcc row_ror:8 row_mask:0xf bank_mask:0xf
	v_cndmask_b32_dpp v49, v43, v49, vcc row_ror:8 row_mask:0xf bank_mask:0xf
	v_cndmask_b32_dpp v40, v34, v40, vcc row_ror:8 row_mask:0xf bank_mask:0xf
	v_cndmask_b32_dpp v41, v35, v41, vcc row_ror:8 row_mask:0xf bank_mask:0xf
	v_cndmask_b32_dpp v32, v26, v32, vcc row_ror:8 row_mask:0xf bank_mask:0xf
	v_cndmask_b32_dpp v33, v27, v33, vcc row_ror:8 row_mask:0xf bank_mask:0xf
	v_cndmask_b32_dpp v24, v18, v24, vcc row_ror:8 row_mask:0xf bank_mask:0xf
	v_cndmask_b32_dpp v25, v19, v25, vcc row_ror:8 row_mask:0xf bank_mask:0xf
	v_cndmask_b32_dpp v16, v10, v16, vcc row_ror:8 row_mask:0xf bank_mask:0xf
	v_cndmask_b32_dpp v17, v11, v17, vcc row_ror:8 row_mask:0xf bank_mask:0xf
	v_cndmask_b32_dpp v8, v2, v8, vcc row_ror:8 row_mask:0xf bank_mask:0xf
	v_cndmask_b32_dpp v9, v3, v9, vcc row_ror:8 row_mask:0xf bank_mask:0xf
	s_mov_b64 vcc, s[64:65]
	s_nop 1
	v_cndmask_b32_dpp v126, v122, v126, vcc row_ror:8 row_mask:0xf bank_mask:0xf
	v_cndmask_b32_dpp v127, v123, v127, vcc row_ror:8 row_mask:0xf bank_mask:0xf
	v_cndmask_b32_dpp v118, v114, v118, vcc row_ror:8 row_mask:0xf bank_mask:0xf
	v_cndmask_b32_dpp v119, v115, v119, vcc row_ror:8 row_mask:0xf bank_mask:0xf
	v_cndmask_b32_dpp v110, v106, v110, vcc row_ror:8 row_mask:0xf bank_mask:0xf
	v_cndmask_b32_dpp v111, v107, v111, vcc row_ror:8 row_mask:0xf bank_mask:0xf
	v_cndmask_b32_dpp v102, v98, v102, vcc row_ror:8 row_mask:0xf bank_mask:0xf
	v_cndmask_b32_dpp v103, v99, v103, vcc row_ror:8 row_mask:0xf bank_mask:0xf
	v_cndmask_b32_dpp v94, v90, v94, vcc row_ror:8 row_mask:0xf bank_mask:0xf
	v_cndmask_b32_dpp v95, v91, v95, vcc row_ror:8 row_mask:0xf bank_mask:0xf
	v_cndmask_b32_dpp v86, v82, v86, vcc row_ror:8 row_mask:0xf bank_mask:0xf
	v_cndmask_b32_dpp v87, v83, v87, vcc row_ror:8 row_mask:0xf bank_mask:0xf
	v_cndmask_b32_dpp v78, v74, v78, vcc row_ror:8 row_mask:0xf bank_mask:0xf
	v_cndmask_b32_dpp v79, v75, v79, vcc row_ror:8 row_mask:0xf bank_mask:0xf
	v_cndmask_b32_dpp v70, v66, v70, vcc row_ror:8 row_mask:0xf bank_mask:0xf
	v_cndmask_b32_dpp v71, v67, v71, vcc row_ror:8 row_mask:0xf bank_mask:0xf
	v_cndmask_b32_dpp v62, v58, v62, vcc row_ror:8 row_mask:0xf bank_mask:0xf
	v_cndmask_b32_dpp v63, v59, v63, vcc row_ror:8 row_mask:0xf bank_mask:0xf
	v_cndmask_b32_dpp v54, v50, v54, vcc row_ror:8 row_mask:0xf bank_mask:0xf
	v_cndmask_b32_dpp v55, v51, v55, vcc row_ror:8 row_mask:0xf bank_mask:0xf
	v_cndmask_b32_dpp v46, v42, v46, vcc row_ror:8 row_mask:0xf bank_mask:0xf
	v_cndmask_b32_dpp v47, v43, v47, vcc row_ror:8 row_mask:0xf bank_mask:0xf
	v_cndmask_b32_dpp v38, v34, v38, vcc row_ror:8 row_mask:0xf bank_mask:0xf
	v_cndmask_b32_dpp v39, v35, v39, vcc row_ror:8 row_mask:0xf bank_mask:0xf
	v_cndmask_b32_dpp v30, v26, v30, vcc row_ror:8 row_mask:0xf bank_mask:0xf
	v_cndmask_b32_dpp v31, v27, v31, vcc row_ror:8 row_mask:0xf bank_mask:0xf
	v_cndmask_b32_dpp v22, v18, v22, vcc row_ror:8 row_mask:0xf bank_mask:0xf
	v_cndmask_b32_dpp v23, v19, v23, vcc row_ror:8 row_mask:0xf bank_mask:0xf
	v_cndmask_b32_dpp v14, v10, v14, vcc row_ror:8 row_mask:0xf bank_mask:0xf
	v_cndmask_b32_dpp v15, v11, v15, vcc row_ror:8 row_mask:0xf bank_mask:0xf
	v_cndmask_b32_dpp v6, v2, v6, vcc row_ror:8 row_mask:0xf bank_mask:0xf
	v_cndmask_b32_dpp v7, v3, v7, vcc row_ror:8 row_mask:0xf bank_mask:0xf
	v_cndmask_b32_e64 v122, v127, v126, s[80:81]
	v_cndmask_b32_e64 v123, v129, v128, s[80:81]
	v_cndmask_b32_e64 v114, v119, v118, s[80:81]
	v_cndmask_b32_e64 v115, v121, v120, s[80:81]
	v_cndmask_b32_e64 v106, v111, v110, s[80:81]
	v_cndmask_b32_e64 v107, v113, v112, s[80:81]
	v_cndmask_b32_e64 v98, v103, v102, s[80:81]
	v_cndmask_b32_e64 v99, v105, v104, s[80:81]
	v_cndmask_b32_e64 v90, v95, v94, s[80:81]
	v_cndmask_b32_e64 v91, v97, v96, s[80:81]
	v_cndmask_b32_e64 v82, v87, v86, s[80:81]
	v_cndmask_b32_e64 v83, v89, v88, s[80:81]
	v_cndmask_b32_e64 v74, v79, v78, s[80:81]
	v_cndmask_b32_e64 v75, v81, v80, s[80:81]
	v_cndmask_b32_e64 v66, v71, v70, s[80:81]
	v_cndmask_b32_e64 v67, v73, v72, s[80:81]
	v_cndmask_b32_e64 v58, v63, v62, s[80:81]
	v_cndmask_b32_e64 v59, v65, v64, s[80:81]
	v_cndmask_b32_e64 v50, v55, v54, s[80:81]
	v_cndmask_b32_e64 v51, v57, v56, s[80:81]
	v_cndmask_b32_e64 v42, v47, v46, s[80:81]
	v_cndmask_b32_e64 v43, v49, v48, s[80:81]
	v_cndmask_b32_e64 v34, v39, v38, s[80:81]
	v_cndmask_b32_e64 v35, v41, v40, s[80:81]
	v_cndmask_b32_e64 v26, v31, v30, s[80:81]
	v_cndmask_b32_e64 v27, v33, v32, s[80:81]
	v_cndmask_b32_e64 v18, v23, v22, s[80:81]
	v_cndmask_b32_e64 v19, v25, v24, s[80:81]
	v_cndmask_b32_e64 v10, v15, v14, s[80:81]
	v_cndmask_b32_e64 v11, v17, v16, s[80:81]
	v_cndmask_b32_e64 v2, v7, v6, s[80:81]
	v_cndmask_b32_e64 v3, v9, v8, s[80:81]
	s_mov_b64 vcc, s[80:81]
	s_nop 1
	v_cndmask_b32_dpp v127, v122, v127, vcc quad_perm:[2,3,0,1] row_mask:0xf bank_mask:0xf
	v_cndmask_b32_dpp v129, v123, v129, vcc quad_perm:[2,3,0,1] row_mask:0xf bank_mask:0xf
	v_cndmask_b32_dpp v119, v114, v119, vcc quad_perm:[2,3,0,1] row_mask:0xf bank_mask:0xf
	v_cndmask_b32_dpp v121, v115, v121, vcc quad_perm:[2,3,0,1] row_mask:0xf bank_mask:0xf
	v_cndmask_b32_dpp v111, v106, v111, vcc quad_perm:[2,3,0,1] row_mask:0xf bank_mask:0xf
	v_cndmask_b32_dpp v113, v107, v113, vcc quad_perm:[2,3,0,1] row_mask:0xf bank_mask:0xf
	v_cndmask_b32_dpp v103, v98, v103, vcc quad_perm:[2,3,0,1] row_mask:0xf bank_mask:0xf
	v_cndmask_b32_dpp v105, v99, v105, vcc quad_perm:[2,3,0,1] row_mask:0xf bank_mask:0xf
	v_cndmask_b32_dpp v95, v90, v95, vcc quad_perm:[2,3,0,1] row_mask:0xf bank_mask:0xf
	v_cndmask_b32_dpp v97, v91, v97, vcc quad_perm:[2,3,0,1] row_mask:0xf bank_mask:0xf
	v_cndmask_b32_dpp v87, v82, v87, vcc quad_perm:[2,3,0,1] row_mask:0xf bank_mask:0xf
	v_cndmask_b32_dpp v89, v83, v89, vcc quad_perm:[2,3,0,1] row_mask:0xf bank_mask:0xf
	v_cndmask_b32_dpp v79, v74, v79, vcc quad_perm:[2,3,0,1] row_mask:0xf bank_mask:0xf
	v_cndmask_b32_dpp v81, v75, v81, vcc quad_perm:[2,3,0,1] row_mask:0xf bank_mask:0xf
	v_cndmask_b32_dpp v71, v66, v71, vcc quad_perm:[2,3,0,1] row_mask:0xf bank_mask:0xf
	v_cndmask_b32_dpp v73, v67, v73, vcc quad_perm:[2,3,0,1] row_mask:0xf bank_mask:0xf
	v_cndmask_b32_dpp v63, v58, v63, vcc quad_perm:[2,3,0,1] row_mask:0xf bank_mask:0xf
	v_cndmask_b32_dpp v65, v59, v65, vcc quad_perm:[2,3,0,1] row_mask:0xf bank_mask:0xf
	v_cndmask_b32_dpp v55, v50, v55, vcc quad_perm:[2,3,0,1] row_mask:0xf bank_mask:0xf
	v_cndmask_b32_dpp v57, v51, v57, vcc quad_perm:[2,3,0,1] row_mask:0xf bank_mask:0xf
	v_cndmask_b32_dpp v47, v42, v47, vcc quad_perm:[2,3,0,1] row_mask:0xf bank_mask:0xf
	v_cndmask_b32_dpp v49, v43, v49, vcc quad_perm:[2,3,0,1] row_mask:0xf bank_mask:0xf
	v_cndmask_b32_dpp v39, v34, v39, vcc quad_perm:[2,3,0,1] row_mask:0xf bank_mask:0xf
	v_cndmask_b32_dpp v41, v35, v41, vcc quad_perm:[2,3,0,1] row_mask:0xf bank_mask:0xf
	v_cndmask_b32_dpp v31, v26, v31, vcc quad_perm:[2,3,0,1] row_mask:0xf bank_mask:0xf
	v_cndmask_b32_dpp v33, v27, v33, vcc quad_perm:[2,3,0,1] row_mask:0xf bank_mask:0xf
	v_cndmask_b32_dpp v23, v18, v23, vcc quad_perm:[2,3,0,1] row_mask:0xf bank_mask:0xf
	v_cndmask_b32_dpp v25, v19, v25, vcc quad_perm:[2,3,0,1] row_mask:0xf bank_mask:0xf
	v_cndmask_b32_dpp v15, v10, v15, vcc quad_perm:[2,3,0,1] row_mask:0xf bank_mask:0xf
	v_cndmask_b32_dpp v17, v11, v17, vcc quad_perm:[2,3,0,1] row_mask:0xf bank_mask:0xf
	v_cndmask_b32_dpp v7, v2, v7, vcc quad_perm:[2,3,0,1] row_mask:0xf bank_mask:0xf
	v_cndmask_b32_dpp v9, v3, v9, vcc quad_perm:[2,3,0,1] row_mask:0xf bank_mask:0xf
	s_mov_b64 vcc, s[98:99]
	s_nop 1
	v_cndmask_b32_dpp v126, v122, v126, vcc quad_perm:[2,3,0,1] row_mask:0xf bank_mask:0xf
	v_cndmask_b32_dpp v128, v123, v128, vcc quad_perm:[2,3,0,1] row_mask:0xf bank_mask:0xf
	v_cndmask_b32_dpp v118, v114, v118, vcc quad_perm:[2,3,0,1] row_mask:0xf bank_mask:0xf
	v_cndmask_b32_dpp v120, v115, v120, vcc quad_perm:[2,3,0,1] row_mask:0xf bank_mask:0xf
	v_cndmask_b32_dpp v110, v106, v110, vcc quad_perm:[2,3,0,1] row_mask:0xf bank_mask:0xf
	v_cndmask_b32_dpp v112, v107, v112, vcc quad_perm:[2,3,0,1] row_mask:0xf bank_mask:0xf
	v_cndmask_b32_dpp v102, v98, v102, vcc quad_perm:[2,3,0,1] row_mask:0xf bank_mask:0xf
	v_cndmask_b32_dpp v104, v99, v104, vcc quad_perm:[2,3,0,1] row_mask:0xf bank_mask:0xf
	v_cndmask_b32_dpp v94, v90, v94, vcc quad_perm:[2,3,0,1] row_mask:0xf bank_mask:0xf
	v_cndmask_b32_dpp v96, v91, v96, vcc quad_perm:[2,3,0,1] row_mask:0xf bank_mask:0xf
	v_cndmask_b32_dpp v86, v82, v86, vcc quad_perm:[2,3,0,1] row_mask:0xf bank_mask:0xf
	v_cndmask_b32_dpp v88, v83, v88, vcc quad_perm:[2,3,0,1] row_mask:0xf bank_mask:0xf
	v_cndmask_b32_dpp v78, v74, v78, vcc quad_perm:[2,3,0,1] row_mask:0xf bank_mask:0xf
	v_cndmask_b32_dpp v80, v75, v80, vcc quad_perm:[2,3,0,1] row_mask:0xf bank_mask:0xf
	v_cndmask_b32_dpp v70, v66, v70, vcc quad_perm:[2,3,0,1] row_mask:0xf bank_mask:0xf
	v_cndmask_b32_dpp v72, v67, v72, vcc quad_perm:[2,3,0,1] row_mask:0xf bank_mask:0xf
	v_cndmask_b32_dpp v62, v58, v62, vcc quad_perm:[2,3,0,1] row_mask:0xf bank_mask:0xf
	v_cndmask_b32_dpp v64, v59, v64, vcc quad_perm:[2,3,0,1] row_mask:0xf bank_mask:0xf
	v_cndmask_b32_dpp v54, v50, v54, vcc quad_perm:[2,3,0,1] row_mask:0xf bank_mask:0xf
	v_cndmask_b32_dpp v56, v51, v56, vcc quad_perm:[2,3,0,1] row_mask:0xf bank_mask:0xf
	v_cndmask_b32_dpp v46, v42, v46, vcc quad_perm:[2,3,0,1] row_mask:0xf bank_mask:0xf
	v_cndmask_b32_dpp v48, v43, v48, vcc quad_perm:[2,3,0,1] row_mask:0xf bank_mask:0xf
	v_cndmask_b32_dpp v38, v34, v38, vcc quad_perm:[2,3,0,1] row_mask:0xf bank_mask:0xf
	v_cndmask_b32_dpp v40, v35, v40, vcc quad_perm:[2,3,0,1] row_mask:0xf bank_mask:0xf
	v_cndmask_b32_dpp v30, v26, v30, vcc quad_perm:[2,3,0,1] row_mask:0xf bank_mask:0xf
	v_cndmask_b32_dpp v32, v27, v32, vcc quad_perm:[2,3,0,1] row_mask:0xf bank_mask:0xf
	v_cndmask_b32_dpp v22, v18, v22, vcc quad_perm:[2,3,0,1] row_mask:0xf bank_mask:0xf
	v_cndmask_b32_dpp v24, v19, v24, vcc quad_perm:[2,3,0,1] row_mask:0xf bank_mask:0xf
	v_cndmask_b32_dpp v14, v10, v14, vcc quad_perm:[2,3,0,1] row_mask:0xf bank_mask:0xf
	v_cndmask_b32_dpp v16, v11, v16, vcc quad_perm:[2,3,0,1] row_mask:0xf bank_mask:0xf
	v_cndmask_b32_dpp v6, v2, v6, vcc quad_perm:[2,3,0,1] row_mask:0xf bank_mask:0xf
	v_cndmask_b32_dpp v8, v3, v8, vcc quad_perm:[2,3,0,1] row_mask:0xf bank_mask:0xf
	s_nop 1
	v_mov_b32_dpp v122, v126 quad_perm:[1,0,3,2] row_mask:0xf bank_mask:0xf
	v_mov_b32_dpp v123, v127 quad_perm:[1,0,3,2] row_mask:0xf bank_mask:0xf
	v_mov_b32_dpp v124, v128 quad_perm:[1,0,3,2] row_mask:0xf bank_mask:0xf
	v_mov_b32_dpp v125, v129 quad_perm:[1,0,3,2] row_mask:0xf bank_mask:0xf
	v_mov_b32_dpp v114, v118 quad_perm:[1,0,3,2] row_mask:0xf bank_mask:0xf
	v_mov_b32_dpp v115, v119 quad_perm:[1,0,3,2] row_mask:0xf bank_mask:0xf
	v_mov_b32_dpp v116, v120 quad_perm:[1,0,3,2] row_mask:0xf bank_mask:0xf
	v_mov_b32_dpp v117, v121 quad_perm:[1,0,3,2] row_mask:0xf bank_mask:0xf
	v_mov_b32_dpp v106, v110 quad_perm:[1,0,3,2] row_mask:0xf bank_mask:0xf
	v_mov_b32_dpp v107, v111 quad_perm:[1,0,3,2] row_mask:0xf bank_mask:0xf
	v_mov_b32_dpp v108, v112 quad_perm:[1,0,3,2] row_mask:0xf bank_mask:0xf
	v_mov_b32_dpp v109, v113 quad_perm:[1,0,3,2] row_mask:0xf bank_mask:0xf
	v_mov_b32_dpp v98, v102 quad_perm:[1,0,3,2] row_mask:0xf bank_mask:0xf
	v_mov_b32_dpp v99, v103 quad_perm:[1,0,3,2] row_mask:0xf bank_mask:0xf
	v_mov_b32_dpp v100, v104 quad_perm:[1,0,3,2] row_mask:0xf bank_mask:0xf
	v_mov_b32_dpp v101, v105 quad_perm:[1,0,3,2] row_mask:0xf bank_mask:0xf
	v_mov_b32_dpp v90, v94 quad_perm:[1,0,3,2] row_mask:0xf bank_mask:0xf
	v_mov_b32_dpp v91, v95 quad_perm:[1,0,3,2] row_mask:0xf bank_mask:0xf
	v_mov_b32_dpp v92, v96 quad_perm:[1,0,3,2] row_mask:0xf bank_mask:0xf
	v_mov_b32_dpp v93, v97 quad_perm:[1,0,3,2] row_mask:0xf bank_mask:0xf
	v_mov_b32_dpp v82, v86 quad_perm:[1,0,3,2] row_mask:0xf bank_mask:0xf
	v_mov_b32_dpp v83, v87 quad_perm:[1,0,3,2] row_mask:0xf bank_mask:0xf
	v_mov_b32_dpp v84, v88 quad_perm:[1,0,3,2] row_mask:0xf bank_mask:0xf
	v_mov_b32_dpp v85, v89 quad_perm:[1,0,3,2] row_mask:0xf bank_mask:0xf
	v_mov_b32_dpp v74, v78 quad_perm:[1,0,3,2] row_mask:0xf bank_mask:0xf
	v_mov_b32_dpp v75, v79 quad_perm:[1,0,3,2] row_mask:0xf bank_mask:0xf
	v_mov_b32_dpp v76, v80 quad_perm:[1,0,3,2] row_mask:0xf bank_mask:0xf
	v_mov_b32_dpp v77, v81 quad_perm:[1,0,3,2] row_mask:0xf bank_mask:0xf
	v_mov_b32_dpp v66, v70 quad_perm:[1,0,3,2] row_mask:0xf bank_mask:0xf
	v_mov_b32_dpp v67, v71 quad_perm:[1,0,3,2] row_mask:0xf bank_mask:0xf
	v_mov_b32_dpp v68, v72 quad_perm:[1,0,3,2] row_mask:0xf bank_mask:0xf
	v_mov_b32_dpp v69, v73 quad_perm:[1,0,3,2] row_mask:0xf bank_mask:0xf
	v_mov_b32_dpp v58, v62 quad_perm:[1,0,3,2] row_mask:0xf bank_mask:0xf
	v_mov_b32_dpp v59, v63 quad_perm:[1,0,3,2] row_mask:0xf bank_mask:0xf
	v_mov_b32_dpp v60, v64 quad_perm:[1,0,3,2] row_mask:0xf bank_mask:0xf
	v_mov_b32_dpp v61, v65 quad_perm:[1,0,3,2] row_mask:0xf bank_mask:0xf
	v_mov_b32_dpp v50, v54 quad_perm:[1,0,3,2] row_mask:0xf bank_mask:0xf
	v_mov_b32_dpp v51, v55 quad_perm:[1,0,3,2] row_mask:0xf bank_mask:0xf
	v_mov_b32_dpp v52, v56 quad_perm:[1,0,3,2] row_mask:0xf bank_mask:0xf
	v_mov_b32_dpp v53, v57 quad_perm:[1,0,3,2] row_mask:0xf bank_mask:0xf
	v_mov_b32_dpp v42, v46 quad_perm:[1,0,3,2] row_mask:0xf bank_mask:0xf
	v_mov_b32_dpp v43, v47 quad_perm:[1,0,3,2] row_mask:0xf bank_mask:0xf
	v_mov_b32_dpp v44, v48 quad_perm:[1,0,3,2] row_mask:0xf bank_mask:0xf
	v_mov_b32_dpp v45, v49 quad_perm:[1,0,3,2] row_mask:0xf bank_mask:0xf
	v_mov_b32_dpp v34, v38 quad_perm:[1,0,3,2] row_mask:0xf bank_mask:0xf
	v_mov_b32_dpp v35, v39 quad_perm:[1,0,3,2] row_mask:0xf bank_mask:0xf
	v_mov_b32_dpp v36, v40 quad_perm:[1,0,3,2] row_mask:0xf bank_mask:0xf
	v_mov_b32_dpp v37, v41 quad_perm:[1,0,3,2] row_mask:0xf bank_mask:0xf
	v_mov_b32_dpp v26, v30 quad_perm:[1,0,3,2] row_mask:0xf bank_mask:0xf
	v_mov_b32_dpp v27, v31 quad_perm:[1,0,3,2] row_mask:0xf bank_mask:0xf
	v_mov_b32_dpp v28, v32 quad_perm:[1,0,3,2] row_mask:0xf bank_mask:0xf
	v_mov_b32_dpp v29, v33 quad_perm:[1,0,3,2] row_mask:0xf bank_mask:0xf
	v_mov_b32_dpp v18, v22 quad_perm:[1,0,3,2] row_mask:0xf bank_mask:0xf
	v_mov_b32_dpp v19, v23 quad_perm:[1,0,3,2] row_mask:0xf bank_mask:0xf
	v_mov_b32_dpp v20, v24 quad_perm:[1,0,3,2] row_mask:0xf bank_mask:0xf
	v_mov_b32_dpp v21, v25 quad_perm:[1,0,3,2] row_mask:0xf bank_mask:0xf
	v_mov_b32_dpp v10, v14 quad_perm:[1,0,3,2] row_mask:0xf bank_mask:0xf
	v_mov_b32_dpp v11, v15 quad_perm:[1,0,3,2] row_mask:0xf bank_mask:0xf
	v_mov_b32_dpp v12, v16 quad_perm:[1,0,3,2] row_mask:0xf bank_mask:0xf
	v_mov_b32_dpp v13, v17 quad_perm:[1,0,3,2] row_mask:0xf bank_mask:0xf
	v_mov_b32_dpp v2, v6 quad_perm:[1,0,3,2] row_mask:0xf bank_mask:0xf
	v_mov_b32_dpp v3, v7 quad_perm:[1,0,3,2] row_mask:0xf bank_mask:0xf
	v_mov_b32_dpp v4, v8 quad_perm:[1,0,3,2] row_mask:0xf bank_mask:0xf
	v_mov_b32_dpp v5, v9 quad_perm:[1,0,3,2] row_mask:0xf bank_mask:0xf
	v_perm_b32 v126, v122, v126, v182
	v_perm_b32 v127, v123, v127, v182
	v_perm_b32 v128, v124, v128, v182
	v_perm_b32 v129, v125, v129, v182
	v_perm_b32 v118, v114, v118, v182
	v_perm_b32 v119, v115, v119, v182
	v_perm_b32 v120, v116, v120, v182
	v_perm_b32 v121, v117, v121, v182
	v_perm_b32 v110, v106, v110, v182
	v_perm_b32 v111, v107, v111, v182
	v_perm_b32 v112, v108, v112, v182
	v_perm_b32 v113, v109, v113, v182
	v_perm_b32 v102, v98, v102, v182
	v_perm_b32 v103, v99, v103, v182
	v_perm_b32 v104, v100, v104, v182
	v_perm_b32 v105, v101, v105, v182
	v_perm_b32 v94, v90, v94, v182
	v_perm_b32 v95, v91, v95, v182
	v_perm_b32 v96, v92, v96, v182
	v_perm_b32 v97, v93, v97, v182
	v_perm_b32 v86, v82, v86, v182
	v_perm_b32 v87, v83, v87, v182
	v_perm_b32 v88, v84, v88, v182
	v_perm_b32 v89, v85, v89, v182
	v_perm_b32 v78, v74, v78, v182
	v_perm_b32 v79, v75, v79, v182
	v_perm_b32 v80, v76, v80, v182
	v_perm_b32 v81, v77, v81, v182
	v_perm_b32 v70, v66, v70, v182
	v_perm_b32 v71, v67, v71, v182
	v_perm_b32 v72, v68, v72, v182
	v_perm_b32 v73, v69, v73, v182
	v_perm_b32 v62, v58, v62, v182
	v_perm_b32 v63, v59, v63, v182
	v_perm_b32 v64, v60, v64, v182
	v_perm_b32 v65, v61, v65, v182
	v_perm_b32 v54, v50, v54, v182
	v_perm_b32 v55, v51, v55, v182
	v_perm_b32 v56, v52, v56, v182
	v_perm_b32 v57, v53, v57, v182
	v_perm_b32 v46, v42, v46, v182
	v_perm_b32 v47, v43, v47, v182
	v_perm_b32 v48, v44, v48, v182
	v_perm_b32 v49, v45, v49, v182
	v_perm_b32 v38, v34, v38, v182
	v_perm_b32 v39, v35, v39, v182
	v_perm_b32 v40, v36, v40, v182
	v_perm_b32 v41, v37, v41, v182
	v_perm_b32 v30, v26, v30, v182
	v_perm_b32 v31, v27, v31, v182
	v_perm_b32 v32, v28, v32, v182
	v_perm_b32 v33, v29, v33, v182
	v_perm_b32 v22, v18, v22, v182
	v_perm_b32 v23, v19, v23, v182
	v_perm_b32 v24, v20, v24, v182
	v_perm_b32 v25, v21, v25, v182
	v_perm_b32 v14, v10, v14, v182
	v_perm_b32 v15, v11, v15, v182
	v_perm_b32 v16, v12, v16, v182
	v_perm_b32 v17, v13, v17, v182
	v_perm_b32 v6, v2, v6, v182
	v_perm_b32 v7, v3, v7, v182
	v_perm_b32 v8, v4, v8, v182
	v_perm_b32 v9, v5, v9, v182
	global_store_dwordx4 v183, v[126:129], s[100:101]
	s_add_u32 s58, s100, 0x80000
	s_addc_u32 s59, s101, 0
	global_store_dwordx4 v183, v[118:121], s[58:59]
	s_add_u32 s58, s100, 0x400
	s_addc_u32 s59, s101, 0
	global_store_dwordx4 v183, v[110:113], s[58:59]
	s_add_u32 s58, s100, 0x80400
	s_addc_u32 s59, s101, 0
	global_store_dwordx4 v183, v[102:105], s[58:59]
	s_add_u32 s58, s100, 0x1000
	s_addc_u32 s59, s101, 0
	global_store_dwordx4 v183, v[94:97], s[58:59]
	s_add_u32 s58, s100, 0x81000
	s_addc_u32 s59, s101, 0
	global_store_dwordx4 v183, v[86:89], s[58:59]
	s_add_u32 s58, s100, 0x1400
	s_addc_u32 s59, s101, 0
	global_store_dwordx4 v183, v[78:81], s[58:59]
	s_add_u32 s58, s100, 0x81400
	s_addc_u32 s59, s101, 0
	global_store_dwordx4 v183, v[70:73], s[58:59]
	s_add_u32 s58, s100, 0x4000
	s_addc_u32 s59, s101, 0
	global_store_dwordx4 v183, v[62:65], s[58:59]
	s_add_u32 s58, s100, 0x84000
	s_addc_u32 s59, s101, 0
	global_store_dwordx4 v183, v[54:57], s[58:59]
	s_add_u32 s58, s100, 0x4400
	s_addc_u32 s59, s101, 0
	global_store_dwordx4 v183, v[46:49], s[58:59]
	s_add_u32 s58, s100, 0x84400
	s_addc_u32 s59, s101, 0
	global_store_dwordx4 v183, v[38:41], s[58:59]
	s_add_u32 s58, s100, 0x5000
	s_addc_u32 s59, s101, 0
	global_store_dwordx4 v183, v[30:33], s[58:59]
	s_add_u32 s58, s100, 0x85000
	s_addc_u32 s59, s101, 0
	global_store_dwordx4 v183, v[22:25], s[58:59]
	s_add_u32 s58, s100, 0x5400
	s_addc_u32 s59, s101, 0
	global_store_dwordx4 v183, v[14:17], s[58:59]
	s_add_u32 s58, s100, 0x85400
	s_addc_u32 s59, s101, 0
	global_store_dwordx4 v183, v[6:9], s[58:59]
	s_branch .LBB0_289

.LBB0_208:
	s_cmp_eq_u32 s59, 0
	s_cbranch_scc1 .Lvt0
	s_ashr_i32 s35, s57, 11
	s_sub_i32 s34, 11, s59
	s_mul_i32 s35, s35, 24
	v_and_b32_e32 v157, 0x7cf, v172
	s_add_i32 s80, s67, s35
	v_lshlrev_b32_e32 v0, s34, v172
	s_ashr_i32 s81, s80, 31
	v_and_b32_e32 v0, 0x7fe, v0
	v_lshrrev_b32_e32 v130, s59, v157
	s_lshl_b64 s[80:81], s[80:81], 18
	v_add_u32_e32 v131, v0, v130
	v_add_u16_e32 v0, v0, v130
	s_add_u32 s92, s16, s80
	v_lshrrev_b16_e32 v0, 1, v0
	v_and_b32_e32 v130, 3, v131
	v_lshlrev_b32_e32 v153, 7, v131
	s_addc_u32 s93, s17, s81
	v_lshlrev_b32_e32 v132, 6, v131
	v_and_or_b32 v133, v0, 4, v130
	v_and_b32_e32 v0, 0x7f000, v153
	v_lshl_add_u64 v[130:131], s[92:93], 0, v[0:1]
	v_and_b32_e32 v0, 0x400, v132
	v_lshl_add_u64 v[130:131], v[130:131], 0, v[0:1]
	v_and_b32_e32 v0, 0x200, v153
	v_lshl_add_u64 v[130:131], v[130:131], 0, v[0:1]
	v_lshlrev_b32_e32 v0, 1, v133
	v_lshl_add_u64 v[130:131], v[130:131], 0, v[0:1]
	v_lshl_add_u64 v[130:131], v[130:131], 0, s[76:77]
	v_mov_b32_e32 v153, v1
	v_lshl_add_u64 v[130:131], v[130:131], 0, v[152:153]
	s_mov_b32 s55, s77
	v_pk_mul_f32 v[174:175], v[128:129], v[156:157] op_sel_hi:[1,0]
	v_pk_mul_f32 v[176:177], v[126:127], v[156:157] op_sel_hi:[1,0]
	v_lshl_add_u64 v[132:133], v[130:131], 0, s[54:55]
	v_pk_mul_f32 v[178:179], v[124:125], v[156:157] op_sel_hi:[1,0]
	v_pk_mul_f32 v[180:181], v[122:123], v[156:157] op_sel_hi:[1,0]
	v_cvt_pk_bf16_f32 v0, v176, v177
	v_cvt_pk_bf16_f32 v159, v174, v175
	s_mov_b32 s47, s77
	v_pk_mul_f32 v[174:175], v[118:119], v[156:157] op_sel_hi:[1,0]
	v_cvt_pk_bf16_f32 v161, v180, v181
	v_cvt_pk_bf16_f32 v163, v178, v179
	global_store_short v[132:133], v0, off
	global_store_short_d16_hi v[132:133], v0, off offset:16
	global_store_short v[132:133], v159, off offset:32
	global_store_short_d16_hi v[132:133], v159, off offset:48
	global_store_short v[132:133], v161, off offset:64
	global_store_short_d16_hi v[132:133], v161, off offset:80
	global_store_short v[132:133], v163, off offset:96
	global_store_short_d16_hi v[132:133], v163, off offset:112
	v_lshl_add_u64 v[130:131], v[130:131], 0, s[46:47]
	v_pk_mul_f32 v[132:133], v[120:121], v[156:157] op_sel_hi:[1,0]
	v_pk_mul_f32 v[176:177], v[116:117], v[156:157] op_sel_hi:[1,0]
	v_pk_mul_f32 v[178:179], v[114:115], v[156:157] op_sel_hi:[1,0]
	v_cvt_pk_bf16_f32 v0, v174, v175
	v_cvt_pk_bf16_f32 v132, v132, v133
	v_cvt_pk_bf16_f32 v133, v178, v179
	v_cvt_pk_bf16_f32 v159, v176, v177
	global_store_short v[130:131], v0, off
	global_store_short_d16_hi v[130:131], v0, off offset:16
	global_store_short v[130:131], v132, off offset:32
	global_store_short_d16_hi v[130:131], v132, off offset:48
	global_store_short v[130:131], v133, off offset:64
	global_store_short_d16_hi v[130:131], v133, off offset:80
	global_store_short v[130:131], v159, off offset:96
	global_store_short_d16_hi v[130:131], v159, off offset:112
	v_or_b32_e32 v0, 16, v157
	v_lshlrev_b32_e32 v130, s34, v0
	v_and_b32_e32 v130, 0x7fe, v130
	v_lshrrev_b32_e32 v0, s59, v0
	v_add_u32_e32 v131, v130, v0
	v_add_u16_e32 v0, v130, v0
	v_lshrrev_b16_e32 v0, 1, v0
	v_and_b32_e32 v130, 3, v131
	v_lshlrev_b32_e32 v159, 7, v131
	v_lshlrev_b32_e32 v132, 6, v131
	v_and_or_b32 v133, v0, 4, v130
	v_and_b32_e32 v0, 0x7f000, v159
	v_lshl_add_u64 v[130:131], s[92:93], 0, v[0:1]
	v_and_b32_e32 v0, 0x400, v132
	v_lshl_add_u64 v[130:131], v[130:131], 0, v[0:1]
	v_and_b32_e32 v0, 0x200, v159
	v_lshl_add_u64 v[130:131], v[130:131], 0, v[0:1]
	v_lshlrev_b32_e32 v0, 1, v133
	v_lshl_add_u64 v[130:131], v[130:131], 0, v[0:1]
	v_lshl_add_u64 v[130:131], v[130:131], 0, s[76:77]
	v_pk_mul_f32 v[174:175], v[112:113], v[158:159] op_sel_hi:[1,0]
	v_lshl_add_u64 v[130:131], v[130:131], 0, v[152:153]
	v_pk_mul_f32 v[176:177], v[110:111], v[158:159] op_sel_hi:[1,0]
	v_pk_mul_f32 v[178:179], v[108:109], v[158:159] op_sel_hi:[1,0]
	v_pk_mul_f32 v[180:181], v[106:107], v[158:159] op_sel_hi:[1,0]
	v_cvt_pk_bf16_f32 v159, v174, v175
	v_lshl_add_u64 v[132:133], v[130:131], 0, s[54:55]
	v_cvt_pk_bf16_f32 v0, v176, v177
	v_pk_mul_f32 v[174:175], v[102:103], v[158:159] op_sel_hi:[1,0]
	v_cvt_pk_bf16_f32 v161, v180, v181
	v_cvt_pk_bf16_f32 v163, v178, v179
	global_store_short v[132:133], v0, off
	global_store_short_d16_hi v[132:133], v0, off offset:16
	global_store_short v[132:133], v159, off offset:32
	global_store_short_d16_hi v[132:133], v159, off offset:48
	global_store_short v[132:133], v161, off offset:64
	global_store_short_d16_hi v[132:133], v161, off offset:80
	global_store_short v[132:133], v163, off offset:96
	global_store_short_d16_hi v[132:133], v163, off offset:112
	v_lshl_add_u64 v[130:131], v[130:131], 0, s[46:47]
	v_pk_mul_f32 v[132:133], v[104:105], v[158:159] op_sel_hi:[1,0]
	v_pk_mul_f32 v[176:177], v[100:101], v[158:159] op_sel_hi:[1,0]
	v_pk_mul_f32 v[178:179], v[98:99], v[158:159] op_sel_hi:[1,0]
	v_cvt_pk_bf16_f32 v0, v174, v175
	v_cvt_pk_bf16_f32 v132, v132, v133
	v_cvt_pk_bf16_f32 v133, v178, v179
	v_cvt_pk_bf16_f32 v159, v176, v177
	global_store_short v[130:131], v0, off
	global_store_short_d16_hi v[130:131], v0, off offset:16
	global_store_short v[130:131], v132, off offset:32
	global_store_short_d16_hi v[130:131], v132, off offset:48
	global_store_short v[130:131], v133, off offset:64
	global_store_short_d16_hi v[130:131], v133, off offset:80
	global_store_short v[130:131], v159, off offset:96
	global_store_short_d16_hi v[130:131], v159, off offset:112
	v_or_b32_e32 v0, 32, v157
	v_lshlrev_b32_e32 v130, s34, v0
	v_and_b32_e32 v130, 0x7fe, v130
	v_lshrrev_b32_e32 v0, s59, v0
	v_add_u32_e32 v131, v130, v0
	v_add_u16_e32 v0, v130, v0
	v_lshrrev_b16_e32 v0, 1, v0
	v_and_b32_e32 v130, 3, v131
	v_lshlrev_b32_e32 v159, 7, v131
	v_lshlrev_b32_e32 v132, 6, v131
	v_and_or_b32 v133, v0, 4, v130
	v_and_b32_e32 v0, 0x7f000, v159
	v_lshl_add_u64 v[130:131], s[92:93], 0, v[0:1]
	v_and_b32_e32 v0, 0x400, v132
	v_lshl_add_u64 v[130:131], v[130:131], 0, v[0:1]
	v_and_b32_e32 v0, 0x200, v159
	v_lshl_add_u64 v[130:131], v[130:131], 0, v[0:1]
	v_lshlrev_b32_e32 v0, 1, v133
	v_lshl_add_u64 v[130:131], v[130:131], 0, v[0:1]
	v_lshl_add_u64 v[130:131], v[130:131], 0, s[76:77]
	v_pk_mul_f32 v[180:181], v[90:91], v[160:161] op_sel_hi:[1,0]
	v_lshl_add_u64 v[130:131], v[130:131], 0, v[152:153]
	v_pk_mul_f32 v[174:175], v[96:97], v[160:161] op_sel_hi:[1,0]
	v_pk_mul_f32 v[176:177], v[94:95], v[160:161] op_sel_hi:[1,0]
	v_pk_mul_f32 v[178:179], v[92:93], v[160:161] op_sel_hi:[1,0]
	v_cvt_pk_bf16_f32 v161, v180, v181
	v_lshl_add_u64 v[132:133], v[130:131], 0, s[54:55]
	v_cvt_pk_bf16_f32 v0, v176, v177
	v_cvt_pk_bf16_f32 v159, v174, v175
	v_pk_mul_f32 v[174:175], v[86:87], v[160:161] op_sel_hi:[1,0]
	v_cvt_pk_bf16_f32 v163, v178, v179
	global_store_short v[132:133], v0, off
	global_store_short_d16_hi v[132:133], v0, off offset:16
	global_store_short v[132:133], v159, off offset:32
	global_store_short_d16_hi v[132:133], v159, off offset:48
	global_store_short v[132:133], v161, off offset:64
	global_store_short_d16_hi v[132:133], v161, off offset:80
	global_store_short v[132:133], v163, off offset:96
	global_store_short_d16_hi v[132:133], v163, off offset:112
	v_lshl_add_u64 v[130:131], v[130:131], 0, s[46:47]
	v_pk_mul_f32 v[132:133], v[88:89], v[160:161] op_sel_hi:[1,0]
	v_pk_mul_f32 v[176:177], v[84:85], v[160:161] op_sel_hi:[1,0]
	v_pk_mul_f32 v[178:179], v[82:83], v[160:161] op_sel_hi:[1,0]
	v_cvt_pk_bf16_f32 v0, v174, v175
	v_cvt_pk_bf16_f32 v132, v132, v133
	v_cvt_pk_bf16_f32 v133, v178, v179
	v_cvt_pk_bf16_f32 v159, v176, v177
	global_store_short v[130:131], v0, off
	global_store_short_d16_hi v[130:131], v0, off offset:16
	global_store_short v[130:131], v132, off offset:32
	global_store_short_d16_hi v[130:131], v132, off offset:48
	global_store_short v[130:131], v133, off offset:64
	global_store_short_d16_hi v[130:131], v133, off offset:80
	global_store_short v[130:131], v159, off offset:96
	global_store_short_d16_hi v[130:131], v159, off offset:112
	v_or_b32_e32 v0, 48, v157
	v_lshlrev_b32_e32 v130, s34, v0
	v_and_b32_e32 v130, 0x7fe, v130
	v_lshrrev_b32_e32 v0, s59, v0
	v_add_u32_e32 v131, v130, v0
	v_add_u16_e32 v0, v130, v0
	v_lshrrev_b16_e32 v0, 1, v0
	v_and_b32_e32 v130, 3, v131
	v_lshlrev_b32_e32 v157, 7, v131
	v_lshlrev_b32_e32 v132, 6, v131
	v_and_or_b32 v133, v0, 4, v130
	v_and_b32_e32 v0, 0x7f000, v157
	v_lshl_add_u64 v[130:131], s[92:93], 0, v[0:1]
	v_and_b32_e32 v0, 0x400, v132
	v_lshl_add_u64 v[130:131], v[130:131], 0, v[0:1]
	v_and_b32_e32 v0, 0x200, v157
	v_lshl_add_u64 v[130:131], v[130:131], 0, v[0:1]
	v_lshlrev_b32_e32 v0, 1, v133
	v_lshl_add_u64 v[130:131], v[130:131], 0, v[0:1]
	v_lshl_add_u64 v[130:131], v[130:131], 0, s[76:77]
	v_lshl_add_u64 v[130:131], v[130:131], 0, v[152:153]
	v_pk_mul_f32 v[174:175], v[80:81], v[162:163] op_sel_hi:[1,0]
	v_pk_mul_f32 v[176:177], v[78:79], v[162:163] op_sel_hi:[1,0]
	v_lshl_add_u64 v[132:133], v[130:131], 0, s[54:55]
	v_pk_mul_f32 v[178:179], v[76:77], v[162:163] op_sel_hi:[1,0]
	v_pk_mul_f32 v[180:181], v[74:75], v[162:163] op_sel_hi:[1,0]
	v_cvt_pk_bf16_f32 v0, v176, v177
	v_cvt_pk_bf16_f32 v157, v174, v175
	v_pk_mul_f32 v[174:175], v[70:71], v[162:163] op_sel_hi:[1,0]
	v_cvt_pk_bf16_f32 v159, v180, v181
	v_cvt_pk_bf16_f32 v161, v178, v179
	global_store_short v[132:133], v0, off
	global_store_short_d16_hi v[132:133], v0, off offset:16
	global_store_short v[132:133], v157, off offset:32
	global_store_short_d16_hi v[132:133], v157, off offset:48
	global_store_short v[132:133], v159, off offset:64
	global_store_short_d16_hi v[132:133], v159, off offset:80
	global_store_short v[132:133], v161, off offset:96
	global_store_short_d16_hi v[132:133], v161, off offset:112
	v_lshl_add_u64 v[130:131], v[130:131], 0, s[46:47]
	v_pk_mul_f32 v[132:133], v[72:73], v[162:163] op_sel_hi:[1,0]
	v_pk_mul_f32 v[176:177], v[68:69], v[162:163] op_sel_hi:[1,0]
	v_pk_mul_f32 v[178:179], v[66:67], v[162:163] op_sel_hi:[1,0]
	v_cvt_pk_bf16_f32 v0, v174, v175
	v_cvt_pk_bf16_f32 v132, v132, v133
	v_cvt_pk_bf16_f32 v133, v178, v179
	v_cvt_pk_bf16_f32 v157, v176, v177
	global_store_short v[130:131], v0, off
	global_store_short_d16_hi v[130:131], v0, off offset:16
	global_store_short v[130:131], v132, off offset:32
	global_store_short_d16_hi v[130:131], v132, off offset:48
	global_store_short v[130:131], v133, off offset:64
	global_store_short_d16_hi v[130:131], v133, off offset:80
	global_store_short v[130:131], v157, off offset:96
	global_store_short_d16_hi v[130:131], v157, off offset:112
	v_add_u32_e32 v0, 0x80, v172
	v_and_b32_e32 v157, 0x7cf, v0
	v_ashrrev_i32_e32 v130, 11, v0
	v_lshlrev_b32_e32 v0, s34, v157
	v_mad_i32_i24 v130, v130, 24, s67
	v_and_b32_e32 v0, 0x7fe, v0
	v_lshrrev_b32_e32 v132, s59, v157
	v_ashrrev_i32_e32 v131, 31, v130
	v_add_u32_e32 v133, v0, v132
	v_add_u16_e32 v0, v0, v132
	v_lshlrev_b64 v[130:131], 18, v[130:131]
	v_lshrrev_b16_e32 v0, 1, v0
	v_and_b32_e32 v132, 3, v133
	v_lshlrev_b32_e32 v163, 7, v133
	v_lshl_add_u64 v[130:131], s[16:17], 0, v[130:131]
	v_lshlrev_b32_e32 v159, 6, v133
	v_and_or_b32 v161, v0, 4, v132
	v_and_b32_e32 v0, 0x7f000, v163
	v_lshl_add_u64 v[132:133], v[130:131], 0, v[0:1]
	v_and_b32_e32 v0, 0x400, v159
	v_lshl_add_u64 v[132:133], v[132:133], 0, v[0:1]
	v_and_b32_e32 v0, 0x200, v163
	v_lshl_add_u64 v[132:133], v[132:133], 0, v[0:1]
	v_lshlrev_b32_e32 v0, 1, v161
	v_lshl_add_u64 v[132:133], v[132:133], 0, v[0:1]
	v_lshl_add_u64 v[132:133], v[132:133], 0, s[76:77]
	v_lshl_add_u64 v[132:133], v[132:133], 0, v[152:153]
	v_pk_mul_f32 v[176:177], v[64:65], v[164:165] op_sel_hi:[1,0]
	v_pk_mul_f32 v[178:179], v[62:63], v[164:165] op_sel_hi:[1,0]
	v_lshl_add_u64 v[174:175], v[132:133], 0, s[54:55]
	v_pk_mul_f32 v[180:181], v[60:61], v[164:165] op_sel_hi:[1,0]
	v_pk_mul_f32 v[182:183], v[58:59], v[164:165] op_sel_hi:[1,0]
	v_cvt_pk_bf16_f32 v0, v178, v179
	v_cvt_pk_bf16_f32 v159, v176, v177
	v_pk_mul_f32 v[176:177], v[54:55], v[164:165] op_sel_hi:[1,0]
	v_cvt_pk_bf16_f32 v161, v182, v183
	v_cvt_pk_bf16_f32 v163, v180, v181
	global_store_short v[174:175], v0, off
	global_store_short_d16_hi v[174:175], v0, off offset:16
	global_store_short v[174:175], v159, off offset:32
	global_store_short_d16_hi v[174:175], v159, off offset:48
	global_store_short v[174:175], v161, off offset:64
	global_store_short_d16_hi v[174:175], v161, off offset:80
	global_store_short v[174:175], v163, off offset:96
	global_store_short_d16_hi v[174:175], v163, off offset:112
	v_lshl_add_u64 v[132:133], v[132:133], 0, s[46:47]
	v_pk_mul_f32 v[174:175], v[56:57], v[164:165] op_sel_hi:[1,0]
	v_pk_mul_f32 v[178:179], v[52:53], v[164:165] op_sel_hi:[1,0]
	v_pk_mul_f32 v[180:181], v[50:51], v[164:165] op_sel_hi:[1,0]
	v_cvt_pk_bf16_f32 v0, v176, v177
	v_cvt_pk_bf16_f32 v159, v174, v175
	v_cvt_pk_bf16_f32 v161, v180, v181
	v_cvt_pk_bf16_f32 v163, v178, v179
	global_store_short v[132:133], v0, off
	global_store_short_d16_hi v[132:133], v0, off offset:16
	global_store_short v[132:133], v159, off offset:32
	global_store_short_d16_hi v[132:133], v159, off offset:48
	global_store_short v[132:133], v161, off offset:64
	global_store_short_d16_hi v[132:133], v161, off offset:80
	global_store_short v[132:133], v163, off offset:96
	global_store_short_d16_hi v[132:133], v163, off offset:112
	v_or_b32_e32 v0, 16, v157
	v_lshlrev_b32_e32 v132, s34, v0
	v_and_b32_e32 v132, 0x7fe, v132
	v_lshrrev_b32_e32 v0, s59, v0
	v_add_u32_e32 v133, v132, v0
	v_add_u16_e32 v0, v132, v0
	v_lshrrev_b16_e32 v0, 1, v0
	v_and_b32_e32 v132, 3, v133
	v_lshlrev_b32_e32 v163, 7, v133
	v_lshlrev_b32_e32 v159, 6, v133
	v_and_or_b32 v161, v0, 4, v132
	v_and_b32_e32 v0, 0x7f000, v163
	v_lshl_add_u64 v[132:133], v[130:131], 0, v[0:1]
	v_and_b32_e32 v0, 0x400, v159
	v_lshl_add_u64 v[132:133], v[132:133], 0, v[0:1]
	v_and_b32_e32 v0, 0x200, v163
	v_lshl_add_u64 v[132:133], v[132:133], 0, v[0:1]
	v_lshlrev_b32_e32 v0, 1, v161
	v_lshl_add_u64 v[132:133], v[132:133], 0, v[0:1]
	v_lshl_add_u64 v[132:133], v[132:133], 0, s[76:77]
	v_lshl_add_u64 v[132:133], v[132:133], 0, v[152:153]
	v_pk_mul_f32 v[176:177], v[48:49], v[166:167] op_sel_hi:[1,0]
	v_pk_mul_f32 v[178:179], v[46:47], v[166:167] op_sel_hi:[1,0]
	v_lshl_add_u64 v[174:175], v[132:133], 0, s[54:55]
	v_pk_mul_f32 v[180:181], v[44:45], v[166:167] op_sel_hi:[1,0]
	v_pk_mul_f32 v[182:183], v[42:43], v[166:167] op_sel_hi:[1,0]
	v_cvt_pk_bf16_f32 v0, v178, v179
	v_cvt_pk_bf16_f32 v159, v176, v177
	v_pk_mul_f32 v[176:177], v[38:39], v[166:167] op_sel_hi:[1,0]
	v_cvt_pk_bf16_f32 v161, v182, v183
	v_cvt_pk_bf16_f32 v163, v180, v181
	global_store_short v[174:175], v0, off
	global_store_short_d16_hi v[174:175], v0, off offset:16
	global_store_short v[174:175], v159, off offset:32
	global_store_short_d16_hi v[174:175], v159, off offset:48
	global_store_short v[174:175], v161, off offset:64
	global_store_short_d16_hi v[174:175], v161, off offset:80
	global_store_short v[174:175], v163, off offset:96
	global_store_short_d16_hi v[174:175], v163, off offset:112
	v_lshl_add_u64 v[132:133], v[132:133], 0, s[46:47]
	v_pk_mul_f32 v[174:175], v[40:41], v[166:167] op_sel_hi:[1,0]
	v_pk_mul_f32 v[178:179], v[36:37], v[166:167] op_sel_hi:[1,0]
	v_pk_mul_f32 v[180:181], v[34:35], v[166:167] op_sel_hi:[1,0]
	v_cvt_pk_bf16_f32 v0, v176, v177
	v_cvt_pk_bf16_f32 v159, v174, v175
	v_cvt_pk_bf16_f32 v161, v180, v181
	v_cvt_pk_bf16_f32 v163, v178, v179
	global_store_short v[132:133], v0, off
	global_store_short_d16_hi v[132:133], v0, off offset:16
	global_store_short v[132:133], v159, off offset:32
	global_store_short_d16_hi v[132:133], v159, off offset:48
	global_store_short v[132:133], v161, off offset:64
	global_store_short_d16_hi v[132:133], v161, off offset:80
	global_store_short v[132:133], v163, off offset:96
	global_store_short_d16_hi v[132:133], v163, off offset:112
	v_or_b32_e32 v0, 32, v157
	v_lshlrev_b32_e32 v132, s34, v0
	v_and_b32_e32 v132, 0x7fe, v132
	v_lshrrev_b32_e32 v0, s59, v0
	v_add_u32_e32 v133, v132, v0
	v_add_u16_e32 v0, v132, v0
	v_lshrrev_b16_e32 v0, 1, v0
	v_and_b32_e32 v132, 3, v133
	v_lshlrev_b32_e32 v163, 7, v133
	v_lshlrev_b32_e32 v159, 6, v133
	v_and_or_b32 v161, v0, 4, v132
	v_and_b32_e32 v0, 0x7f000, v163
	v_lshl_add_u64 v[132:133], v[130:131], 0, v[0:1]
	v_and_b32_e32 v0, 0x400, v159
	v_lshl_add_u64 v[132:133], v[132:133], 0, v[0:1]
	v_and_b32_e32 v0, 0x200, v163
	v_lshl_add_u64 v[132:133], v[132:133], 0, v[0:1]
	v_lshlrev_b32_e32 v0, 1, v161
	v_lshl_add_u64 v[132:133], v[132:133], 0, v[0:1]
	v_lshl_add_u64 v[132:133], v[132:133], 0, s[76:77]
	v_lshl_add_u64 v[132:133], v[132:133], 0, v[152:153]
	v_pk_mul_f32 v[176:177], v[32:33], v[168:169] op_sel_hi:[1,0]
	v_pk_mul_f32 v[178:179], v[30:31], v[168:169] op_sel_hi:[1,0]
	v_lshl_add_u64 v[174:175], v[132:133], 0, s[54:55]
	v_pk_mul_f32 v[180:181], v[28:29], v[168:169] op_sel_hi:[1,0]
	v_pk_mul_f32 v[182:183], v[26:27], v[168:169] op_sel_hi:[1,0]
	v_cvt_pk_bf16_f32 v0, v178, v179
	v_cvt_pk_bf16_f32 v159, v176, v177
	v_pk_mul_f32 v[176:177], v[22:23], v[168:169] op_sel_hi:[1,0]
	v_cvt_pk_bf16_f32 v161, v182, v183
	v_cvt_pk_bf16_f32 v163, v180, v181
	global_store_short v[174:175], v0, off
	global_store_short_d16_hi v[174:175], v0, off offset:16
	global_store_short v[174:175], v159, off offset:32
	global_store_short_d16_hi v[174:175], v159, off offset:48
	global_store_short v[174:175], v161, off offset:64
	global_store_short_d16_hi v[174:175], v161, off offset:80
	global_store_short v[174:175], v163, off offset:96
	global_store_short_d16_hi v[174:175], v163, off offset:112
	v_lshl_add_u64 v[132:133], v[132:133], 0, s[46:47]
	v_pk_mul_f32 v[174:175], v[24:25], v[168:169] op_sel_hi:[1,0]
	v_pk_mul_f32 v[178:179], v[20:21], v[168:169] op_sel_hi:[1,0]
	v_pk_mul_f32 v[180:181], v[18:19], v[168:169] op_sel_hi:[1,0]
	v_cvt_pk_bf16_f32 v0, v176, v177
	v_cvt_pk_bf16_f32 v159, v174, v175
	v_cvt_pk_bf16_f32 v161, v180, v181
	v_cvt_pk_bf16_f32 v163, v178, v179
	global_store_short v[132:133], v0, off
	global_store_short_d16_hi v[132:133], v0, off offset:16
	global_store_short v[132:133], v159, off offset:32
	global_store_short_d16_hi v[132:133], v159, off offset:48
	global_store_short v[132:133], v161, off offset:64
	global_store_short_d16_hi v[132:133], v161, off offset:80
	global_store_short v[132:133], v163, off offset:96
	global_store_short_d16_hi v[132:133], v163, off offset:112
	v_or_b32_e32 v0, 48, v157
	v_lshlrev_b32_e32 v132, s34, v0
	v_and_b32_e32 v132, 0x7fe, v132
	v_lshrrev_b32_e32 v0, s59, v0
	v_add_u32_e32 v133, v132, v0
	v_add_u16_e32 v0, v132, v0
	v_lshlrev_b32_e32 v157, 6, v133
	v_lshrrev_b16_e32 v0, 1, v0
	v_and_b32_e32 v132, 3, v133
	v_lshlrev_b32_e32 v133, 7, v133
	v_and_or_b32 v132, v0, 4, v132
	v_and_b32_e32 v0, 0x7f000, v133
	v_lshl_add_u64 v[130:131], v[130:131], 0, v[0:1]
	v_and_b32_e32 v0, 0x400, v157
	v_lshl_add_u64 v[130:131], v[130:131], 0, v[0:1]
	v_and_b32_e32 v0, 0x200, v133
	v_lshl_add_u64 v[130:131], v[130:131], 0, v[0:1]
	v_lshlrev_b32_e32 v0, 1, v132
	v_lshl_add_u64 v[130:131], v[130:131], 0, v[0:1]
	v_lshl_add_u64 v[130:131], v[130:131], 0, s[76:77]
	v_lshl_add_u64 v[130:131], v[130:131], 0, v[152:153]
	v_pk_mul_f32 v[174:175], v[16:17], v[170:171] op_sel_hi:[1,0]
	v_pk_mul_f32 v[176:177], v[14:15], v[170:171] op_sel_hi:[1,0]
	v_lshl_add_u64 v[132:133], v[130:131], 0, s[54:55]
	v_pk_mul_f32 v[178:179], v[12:13], v[170:171] op_sel_hi:[1,0]
	v_pk_mul_f32 v[180:181], v[10:11], v[170:171] op_sel_hi:[1,0]
	v_cvt_pk_bf16_f32 v0, v176, v177
	v_cvt_pk_bf16_f32 v153, v174, v175
	v_pk_mul_f32 v[174:175], v[6:7], v[170:171] op_sel_hi:[1,0]
	v_cvt_pk_bf16_f32 v157, v180, v181
	v_cvt_pk_bf16_f32 v159, v178, v179
	global_store_short v[132:133], v0, off
	global_store_short_d16_hi v[132:133], v0, off offset:16
	global_store_short v[132:133], v153, off offset:32
	global_store_short_d16_hi v[132:133], v153, off offset:48
	global_store_short v[132:133], v157, off offset:64
	global_store_short_d16_hi v[132:133], v157, off offset:80
	global_store_short v[132:133], v159, off offset:96
	global_store_short_d16_hi v[132:133], v159, off offset:112
	v_lshl_add_u64 v[130:131], v[130:131], 0, s[46:47]
	v_pk_mul_f32 v[132:133], v[8:9], v[170:171] op_sel_hi:[1,0]
	v_pk_mul_f32 v[176:177], v[4:5], v[170:171] op_sel_hi:[1,0]
	v_pk_mul_f32 v[178:179], v[2:3], v[170:171] op_sel_hi:[1,0]
	v_cvt_pk_bf16_f32 v0, v174, v175
	s_mov_b64 s[92:93], 0
	v_cvt_pk_bf16_f32 v132, v132, v133
	v_cvt_pk_bf16_f32 v133, v178, v179
	v_cvt_pk_bf16_f32 v153, v176, v177
	global_store_short v[130:131], v0, off
	global_store_short_d16_hi v[130:131], v0, off offset:16
	global_store_short v[130:131], v132, off offset:32
	global_store_short_d16_hi v[130:131], v132, off offset:48
	global_store_short v[130:131], v133, off offset:64
	global_store_short_d16_hi v[130:131], v133, off offset:80
	global_store_short v[130:131], v153, off offset:96
	global_store_short_d16_hi v[130:131], v153, off offset:112
	s_andn2_b64 vcc, exec, s[6:7]
	s_cbranch_vccz .LBB0_217
